# NSA top-k: replaced 13-round cross-lane argmax loop with exact radix-select (threshold binary search via ballot popcounts), same selection set and tie rule
# speedup vs baseline: 1.0485x; 1.0235x over previous
; __device__ __forceinline__ void nsa_attn_phase(unsigned char* big, bf16_t* outO, LAS unsigned char* lds) {
;     ...
;         {
;             float v0[8], v1[8], v2[8], v3[8]; unsigned sb[8];
;             const bool big16 = cur >= 16;
; #pragma unroll
;             for (int qq = 0; qq < 8; ++qq) {
;                 const LAS float* row = impw + qq * 256; const int j0 = lane, j1 = lane + 64, j2 = lane + 128, j3 = lane + 192;
;                 v0[qq] = (big16 && j0 >= 1 && j0 <= cur - 2) ? row[j0] : -1.f; v1[qq] = (big16 && j1 <= cur - 2) ? row[j1] : -1.f;
;                 v2[qq] = (big16 && j2 <= cur - 2) ? row[j2] : -1.f; v3[qq] = (big16 && j3 <= cur - 2) ? row[j3] : -1.f; sb[qq] = 0u;
;             }
;             if (big16) {
;                 for (int rr = 0; rr < 13; ++rr) {
;                     float best[8]; int bj[8];
; #pragma unroll
;                     for (int qq = 0; qq < 8; ++qq) {
;                         best[qq] = v0[qq]; bj[qq] = lane;
;                         if (v1[qq] > best[qq]) { best[qq] = v1[qq]; bj[qq] = lane + 64; }
;                         if (v2[qq] > best[qq]) { best[qq] = v2[qq]; bj[qq] = lane + 128; }
;                         if (v3[qq] > best[qq]) { best[qq] = v3[qq]; bj[qq] = lane + 192; }
;                     }
; #pragma unroll
;                     for (int off = 32; off >= 1; off >>= 1) {
;                         float ov[8]; int oj[8];
; #pragma unroll
;                         for (int qq = 0; qq < 8; ++qq) { ov[qq] = __shfl_xor(best[qq], off); oj[qq] = __shfl_xor(bj[qq], off); }
; #pragma unroll
;                         for (int qq = 0; qq < 8; ++qq) if (ov[qq] > best[qq] || (ov[qq] == best[qq] && oj[qq] < bj[qq])) { best[qq] = ov[qq]; bj[qq] = oj[qq]; }
;                     }
; #pragma unroll
;                     for (int qq = 0; qq < 8; ++qq) if ((bj[qq] & 63) == lane) { const int e = bj[qq] >> 6;
;                         if (e == 0) { v0[qq] = -2.f; sb[qq] |= 1u; } else if (e == 1) { v1[qq] = -2.f; sb[qq] |= 2u; } else if (e == 2) { v2[qq] = -2.f; sb[qq] |= 4u; } else { v3[qq] = -2.f; sb[qq] |= 8u; } }
;                 }
;             }
; #pragma unroll
;             for (int qq = 0; qq < 8; ++qq) {
; #pragma unroll
;                 for (int e = 0; e < 4; ++e) { const int j = lane + 64 * e; const bool f = (cur < 16) ? (j <= cur) : (j == 0 || j == cur || j == cur - 1); if (f) sb[qq] |= (1u << e); }
.LBB0_960:
	s_waitcnt lgkmcnt(0)
	s_cmp_lt_i32 s55, 16
	s_cbranch_scc1 .Ltk_small
	ds_read_b32 v64, v186
	ds_read_b32 v65, v186 offset:256
	ds_read_b32 v66, v186 offset:512
	ds_read_b32 v67, v186 offset:768
	ds_read_b32 v68, v186 offset:1024
	ds_read_b32 v69, v186 offset:1280
	ds_read_b32 v70, v186 offset:1536
	ds_read_b32 v71, v186 offset:1792
	ds_read_b32 v72, v186 offset:2048
	ds_read_b32 v73, v186 offset:2304
	ds_read_b32 v74, v186 offset:2560
	ds_read_b32 v75, v186 offset:2816
	ds_read_b32 v76, v186 offset:3072
	ds_read_b32 v77, v186 offset:3328
	ds_read_b32 v78, v186 offset:3584
	ds_read_b32 v79, v186 offset:3840
	ds_read_b32 v80, v186 offset:4096
	ds_read_b32 v81, v186 offset:4352
	ds_read_b32 v82, v186 offset:4608
	ds_read_b32 v83, v186 offset:4864
	ds_read_b32 v84, v186 offset:5120
	ds_read_b32 v85, v186 offset:5376
	ds_read_b32 v86, v186 offset:5632
	ds_read_b32 v87, v186 offset:5888
	ds_read_b32 v88, v186 offset:6144
	ds_read_b32 v89, v186 offset:6400
	ds_read_b32 v90, v186 offset:6656
	ds_read_b32 v91, v186 offset:6912
	ds_read_b32 v92, v186 offset:7168
	ds_read_b32 v93, v186 offset:7424
	ds_read_b32 v94, v186 offset:7680
	ds_read_b32 v95, v186 offset:7936
	s_add_i32 s87, s55, -2
	s_add_i32 s88, s55, -1
	v_bfrev_b32_e32 v108, 1
	v_not_b32_e32 v109, v108
	v_cmp_le_i32_e64 s[34:35], 1, v151
	v_cmp_ge_i32_e64 s[90:91], s87, v151
	s_and_b64 s[34:35], s[34:35], s[90:91]
	v_cmp_eq_u32_e64 s[20:21], 0, v151
	v_cmp_eq_u32_e64 s[90:91], s55, v151
	s_or_b64 s[20:21], s[20:21], s[90:91]
	v_cmp_eq_u32_e64 s[90:91], s88, v151
	s_or_b64 s[20:21], s[20:21], s[90:91]
	s_nop 1
	v_cndmask_b32_e64 v100, 0, -1, s[34:35]
	v_cndmask_b32_e64 v104, v108, 0, s[34:35]
	v_cndmask_b32_e64 v104, v104, v109, s[20:21]
	v_cmp_le_i32_e64 s[34:35], 1, v176
	v_cmp_ge_i32_e64 s[90:91], s87, v176
	s_and_b64 s[34:35], s[34:35], s[90:91]
	v_cmp_eq_u32_e64 s[20:21], 0, v176
	v_cmp_eq_u32_e64 s[90:91], s55, v176
	s_or_b64 s[20:21], s[20:21], s[90:91]
	v_cmp_eq_u32_e64 s[90:91], s88, v176
	s_or_b64 s[20:21], s[20:21], s[90:91]
	s_nop 1
	v_cndmask_b32_e64 v101, 0, -1, s[34:35]
	v_cndmask_b32_e64 v105, v108, 0, s[34:35]
	v_cndmask_b32_e64 v105, v105, v109, s[20:21]
	v_cmp_le_i32_e64 s[34:35], 1, v177
	v_cmp_ge_i32_e64 s[90:91], s87, v177
	s_and_b64 s[34:35], s[34:35], s[90:91]
	v_cmp_eq_u32_e64 s[20:21], 0, v177
	v_cmp_eq_u32_e64 s[90:91], s55, v177
	s_or_b64 s[20:21], s[20:21], s[90:91]
	v_cmp_eq_u32_e64 s[90:91], s88, v177
	s_or_b64 s[20:21], s[20:21], s[90:91]
	s_nop 1
	v_cndmask_b32_e64 v102, 0, -1, s[34:35]
	v_cndmask_b32_e64 v106, v108, 0, s[34:35]
	v_cndmask_b32_e64 v106, v106, v109, s[20:21]
	v_cmp_le_i32_e64 s[34:35], 1, v178
	v_cmp_ge_i32_e64 s[90:91], s87, v178
	s_and_b64 s[34:35], s[34:35], s[90:91]
	v_cmp_eq_u32_e64 s[20:21], 0, v178
	v_cmp_eq_u32_e64 s[90:91], s55, v178
	s_or_b64 s[20:21], s[20:21], s[90:91]
	v_cmp_eq_u32_e64 s[90:91], s88, v178
	s_or_b64 s[20:21], s[20:21], s[90:91]
	s_nop 1
	v_cndmask_b32_e64 v103, 0, -1, s[34:35]
	v_cndmask_b32_e64 v107, v108, 0, s[34:35]
	v_cndmask_b32_e64 v107, v107, v109, s[20:21]
	s_waitcnt lgkmcnt(0)
	v_and_or_b32 v64, v64, v100, v104
	v_and_or_b32 v65, v65, v101, v105
	v_and_or_b32 v66, v66, v102, v106
	v_and_or_b32 v67, v67, v103, v107
	v_and_or_b32 v68, v68, v100, v104
	v_and_or_b32 v69, v69, v101, v105
	v_and_or_b32 v70, v70, v102, v106
	v_and_or_b32 v71, v71, v103, v107
	v_and_or_b32 v72, v72, v100, v104
	v_and_or_b32 v73, v73, v101, v105
	v_and_or_b32 v74, v74, v102, v106
	v_and_or_b32 v75, v75, v103, v107
	v_and_or_b32 v76, v76, v100, v104
	v_and_or_b32 v77, v77, v101, v105
	v_and_or_b32 v78, v78, v102, v106
	v_and_or_b32 v79, v79, v103, v107
	v_and_or_b32 v80, v80, v100, v104
	v_and_or_b32 v81, v81, v101, v105
	v_and_or_b32 v82, v82, v102, v106
	v_and_or_b32 v83, v83, v103, v107
	v_and_or_b32 v84, v84, v100, v104
	v_and_or_b32 v85, v85, v101, v105
	v_and_or_b32 v86, v86, v102, v106
	v_and_or_b32 v87, v87, v103, v107
	v_and_or_b32 v88, v88, v100, v104
	v_and_or_b32 v89, v89, v101, v105
	v_and_or_b32 v90, v90, v102, v106
	v_and_or_b32 v91, v91, v103, v107
	v_and_or_b32 v92, v92, v100, v104
	v_and_or_b32 v93, v93, v101, v105
	v_and_or_b32 v94, v94, v102, v106
	v_and_or_b32 v95, v95, v103, v107
	s_mov_b32 s38, 0
	s_mov_b32 s39, 0x40000000
.Ltk_q0:
	s_or_b32 s50, s38, s39
	v_cmp_le_i32_e64 s[12:13], s50, v64
	v_cmp_le_i32_e64 s[14:15], s50, v65
	v_cmp_le_i32_e64 s[16:17], s50, v66
	v_cmp_le_i32_e64 s[18:19], s50, v67
	s_bcnt1_i32_b64 s51, s[12:13]
	s_bcnt1_i32_b64 s32, s[14:15]
	s_add_i32 s51, s51, s32
	s_bcnt1_i32_b64 s32, s[16:17]
	s_add_i32 s51, s51, s32
	s_bcnt1_i32_b64 s32, s[18:19]
	s_add_i32 s51, s51, s32
	s_cmp_ge_u32 s51, 16
	s_cselect_b32 s38, s50, s38
	s_lshr_b32 s39, s39, 1
	s_cmp_lg_u32 s39, 0
	s_cbranch_scc1 .Ltk_q0
	v_cmp_lt_i32_e64 s[12:13], s38, v64
	v_cmp_lt_i32_e64 s[14:15], s38, v65
	v_cmp_lt_i32_e64 s[16:17], s38, v66
	v_cmp_lt_i32_e64 s[18:19], s38, v67
	s_bcnt1_i32_b64 s51, s[12:13]
	s_bcnt1_i32_b64 s32, s[14:15]
	s_add_i32 s51, s51, s32
	s_bcnt1_i32_b64 s32, s[16:17]
	s_add_i32 s51, s51, s32
	s_bcnt1_i32_b64 s32, s[18:19]
	s_add_i32 s51, s51, s32
	s_sub_i32 s86, 16, s51
	v_cmp_eq_u32_e64 s[20:21], s38, v64
	s_bcnt1_i32_b64 s32, s[20:21]
	s_nop 1
	v_mbcnt_lo_u32_b32 v110, s20, 0
	v_mbcnt_hi_u32_b32 v110, s21, v110
	v_cmp_gt_u32_e64 s[34:35], s86, v110
	s_and_b64 s[34:35], s[34:35], s[20:21]
	s_or_b64 s[12:13], s[12:13], s[34:35]
	s_sub_i32 s86, s86, s32
	s_max_i32 s86, s86, 0
	v_cmp_eq_u32_e64 s[20:21], s38, v65
	s_bcnt1_i32_b64 s32, s[20:21]
	s_nop 1
	v_mbcnt_lo_u32_b32 v110, s20, 0
	v_mbcnt_hi_u32_b32 v110, s21, v110
	v_cmp_gt_u32_e64 s[34:35], s86, v110
	s_and_b64 s[34:35], s[34:35], s[20:21]
	s_or_b64 s[14:15], s[14:15], s[34:35]
	s_sub_i32 s86, s86, s32
	s_max_i32 s86, s86, 0
	v_cmp_eq_u32_e64 s[20:21], s38, v66
	s_bcnt1_i32_b64 s32, s[20:21]
	s_nop 1
	v_mbcnt_lo_u32_b32 v110, s20, 0
	v_mbcnt_hi_u32_b32 v110, s21, v110
	v_cmp_gt_u32_e64 s[34:35], s86, v110
	s_and_b64 s[34:35], s[34:35], s[20:21]
	s_or_b64 s[16:17], s[16:17], s[34:35]
	s_sub_i32 s86, s86, s32
	s_max_i32 s86, s86, 0
	v_cmp_eq_u32_e64 s[20:21], s38, v67
	s_bcnt1_i32_b64 s32, s[20:21]
	s_nop 1
	v_mbcnt_lo_u32_b32 v110, s20, 0
	v_mbcnt_hi_u32_b32 v110, s21, v110
	v_cmp_gt_u32_e64 s[34:35], s86, v110
	s_and_b64 s[34:35], s[34:35], s[20:21]
	s_or_b64 s[18:19], s[18:19], s[34:35]
	s_sub_i32 s86, s86, s32
	s_max_i32 s86, s86, 0
	s_nop 1
	v_writelane_b32 v96, s12, 0
	v_writelane_b32 v97, s13, 0
	v_writelane_b32 v96, s14, 1
	v_writelane_b32 v97, s15, 1
	v_writelane_b32 v96, s16, 2
	v_writelane_b32 v97, s17, 2
	v_writelane_b32 v96, s18, 3
	v_writelane_b32 v97, s19, 3
	s_mov_b32 s38, 0
	s_mov_b32 s39, 0x40000000
; __device__ __forceinline__ void nsa_attn_phase(unsigned char* big, bf16_t* outO, LAS unsigned char* lds) {
;     ...
;                 for (int rr = 0; rr < 13; ++rr) {
;                     float best[8]; int bj[8];
; #pragma unroll
;                     for (int qq = 0; qq < 8; ++qq) {
;                         best[qq] = v0[qq]; bj[qq] = lane;
;                         if (v1[qq] > best[qq]) { best[qq] = v1[qq]; bj[qq] = lane + 64; }
;                         if (v2[qq] > best[qq]) { best[qq] = v2[qq]; bj[qq] = lane + 128; }
;                         if (v3[qq] > best[qq]) { best[qq] = v3[qq]; bj[qq] = lane + 192; }
;                     }
; #pragma unroll
;                     for (int off = 32; off >= 1; off >>= 1) {
;                         float ov[8]; int oj[8];
; #pragma unroll
;                         for (int qq = 0; qq < 8; ++qq) { ov[qq] = __shfl_xor(best[qq], off); oj[qq] = __shfl_xor(bj[qq], off); }
; #pragma unroll
;                         for (int qq = 0; qq < 8; ++qq) if (ov[qq] > best[qq] || (ov[qq] == best[qq] && oj[qq] < bj[qq])) { best[qq] = ov[qq]; bj[qq] = oj[qq]; }
;                     }
; #pragma unroll
;                     for (int qq = 0; qq < 8; ++qq) if ((bj[qq] & 63) == lane) { const int e = bj[qq] >> 6;
;                         if (e == 0) { v0[qq] = -2.f; sb[qq] |= 1u; } else if (e == 1) { v1[qq] = -2.f; sb[qq] |= 2u; } else if (e == 2) { v2[qq] = -2.f; sb[qq] |= 4u; } else { v3[qq] = -2.f; sb[qq] |= 8u; } }
;                 }
.Ltk_q1:
	s_or_b32 s50, s38, s39
	v_cmp_le_i32_e64 s[12:13], s50, v68
	v_cmp_le_i32_e64 s[14:15], s50, v69
	v_cmp_le_i32_e64 s[16:17], s50, v70
	v_cmp_le_i32_e64 s[18:19], s50, v71
	s_bcnt1_i32_b64 s51, s[12:13]
	s_bcnt1_i32_b64 s32, s[14:15]
	s_add_i32 s51, s51, s32
	s_bcnt1_i32_b64 s32, s[16:17]
	s_add_i32 s51, s51, s32
	s_bcnt1_i32_b64 s32, s[18:19]
	s_add_i32 s51, s51, s32
	s_cmp_ge_u32 s51, 16
	s_cselect_b32 s38, s50, s38
	s_lshr_b32 s39, s39, 1
	s_cmp_lg_u32 s39, 0
	s_cbranch_scc1 .Ltk_q1
	v_cmp_lt_i32_e64 s[12:13], s38, v68
	v_cmp_lt_i32_e64 s[14:15], s38, v69
	v_cmp_lt_i32_e64 s[16:17], s38, v70
	v_cmp_lt_i32_e64 s[18:19], s38, v71
	s_bcnt1_i32_b64 s51, s[12:13]
	s_bcnt1_i32_b64 s32, s[14:15]
	s_add_i32 s51, s51, s32
	s_bcnt1_i32_b64 s32, s[16:17]
	s_add_i32 s51, s51, s32
	s_bcnt1_i32_b64 s32, s[18:19]
	s_add_i32 s51, s51, s32
	s_sub_i32 s86, 16, s51
	v_cmp_eq_u32_e64 s[20:21], s38, v68
	s_bcnt1_i32_b64 s32, s[20:21]
	s_nop 1
	v_mbcnt_lo_u32_b32 v110, s20, 0
	v_mbcnt_hi_u32_b32 v110, s21, v110
	v_cmp_gt_u32_e64 s[34:35], s86, v110
	s_and_b64 s[34:35], s[34:35], s[20:21]
	s_or_b64 s[12:13], s[12:13], s[34:35]
	s_sub_i32 s86, s86, s32
	s_max_i32 s86, s86, 0
	v_cmp_eq_u32_e64 s[20:21], s38, v69
	s_bcnt1_i32_b64 s32, s[20:21]
	s_nop 1
	v_mbcnt_lo_u32_b32 v110, s20, 0
	v_mbcnt_hi_u32_b32 v110, s21, v110
	v_cmp_gt_u32_e64 s[34:35], s86, v110
	s_and_b64 s[34:35], s[34:35], s[20:21]
	s_or_b64 s[14:15], s[14:15], s[34:35]
	s_sub_i32 s86, s86, s32
	s_max_i32 s86, s86, 0
	v_cmp_eq_u32_e64 s[20:21], s38, v70
	s_bcnt1_i32_b64 s32, s[20:21]
	s_nop 1
	v_mbcnt_lo_u32_b32 v110, s20, 0
	v_mbcnt_hi_u32_b32 v110, s21, v110
	v_cmp_gt_u32_e64 s[34:35], s86, v110
	s_and_b64 s[34:35], s[34:35], s[20:21]
	s_or_b64 s[16:17], s[16:17], s[34:35]
	s_sub_i32 s86, s86, s32
	s_max_i32 s86, s86, 0
	v_cmp_eq_u32_e64 s[20:21], s38, v71
	s_bcnt1_i32_b64 s32, s[20:21]
	s_nop 1
	v_mbcnt_lo_u32_b32 v110, s20, 0
	v_mbcnt_hi_u32_b32 v110, s21, v110
	v_cmp_gt_u32_e64 s[34:35], s86, v110
	s_and_b64 s[34:35], s[34:35], s[20:21]
	s_or_b64 s[18:19], s[18:19], s[34:35]
	s_sub_i32 s86, s86, s32
	s_max_i32 s86, s86, 0
	s_nop 1
	v_writelane_b32 v96, s12, 4
	v_writelane_b32 v97, s13, 4
	v_writelane_b32 v96, s14, 5
	v_writelane_b32 v97, s15, 5
	v_writelane_b32 v96, s16, 6
	v_writelane_b32 v97, s17, 6
	v_writelane_b32 v96, s18, 7
	v_writelane_b32 v97, s19, 7
	s_mov_b32 s38, 0
	s_mov_b32 s39, 0x40000000
.Ltk_q2:
	s_or_b32 s50, s38, s39
	v_cmp_le_i32_e64 s[12:13], s50, v72
	v_cmp_le_i32_e64 s[14:15], s50, v73
	v_cmp_le_i32_e64 s[16:17], s50, v74
	v_cmp_le_i32_e64 s[18:19], s50, v75
	s_bcnt1_i32_b64 s51, s[12:13]
	s_bcnt1_i32_b64 s32, s[14:15]
	s_add_i32 s51, s51, s32
	s_bcnt1_i32_b64 s32, s[16:17]
	s_add_i32 s51, s51, s32
	s_bcnt1_i32_b64 s32, s[18:19]
	s_add_i32 s51, s51, s32
	s_cmp_ge_u32 s51, 16
	s_cselect_b32 s38, s50, s38
	s_lshr_b32 s39, s39, 1
	s_cmp_lg_u32 s39, 0
	s_cbranch_scc1 .Ltk_q2
	v_cmp_lt_i32_e64 s[12:13], s38, v72
	v_cmp_lt_i32_e64 s[14:15], s38, v73
	v_cmp_lt_i32_e64 s[16:17], s38, v74
	v_cmp_lt_i32_e64 s[18:19], s38, v75
	s_bcnt1_i32_b64 s51, s[12:13]
	s_bcnt1_i32_b64 s32, s[14:15]
	s_add_i32 s51, s51, s32
	s_bcnt1_i32_b64 s32, s[16:17]
	s_add_i32 s51, s51, s32
	s_bcnt1_i32_b64 s32, s[18:19]
	s_add_i32 s51, s51, s32
	s_sub_i32 s86, 16, s51
	v_cmp_eq_u32_e64 s[20:21], s38, v72
	s_bcnt1_i32_b64 s32, s[20:21]
	s_nop 1
	v_mbcnt_lo_u32_b32 v110, s20, 0
	v_mbcnt_hi_u32_b32 v110, s21, v110
	v_cmp_gt_u32_e64 s[34:35], s86, v110
	s_and_b64 s[34:35], s[34:35], s[20:21]
	s_or_b64 s[12:13], s[12:13], s[34:35]
	s_sub_i32 s86, s86, s32
	s_max_i32 s86, s86, 0
	v_cmp_eq_u32_e64 s[20:21], s38, v73
	s_bcnt1_i32_b64 s32, s[20:21]
	s_nop 1
	v_mbcnt_lo_u32_b32 v110, s20, 0
	v_mbcnt_hi_u32_b32 v110, s21, v110
	v_cmp_gt_u32_e64 s[34:35], s86, v110
	s_and_b64 s[34:35], s[34:35], s[20:21]
	s_or_b64 s[14:15], s[14:15], s[34:35]
	s_sub_i32 s86, s86, s32
	s_max_i32 s86, s86, 0
	v_cmp_eq_u32_e64 s[20:21], s38, v74
	s_bcnt1_i32_b64 s32, s[20:21]
	s_nop 1
	v_mbcnt_lo_u32_b32 v110, s20, 0
	v_mbcnt_hi_u32_b32 v110, s21, v110
	v_cmp_gt_u32_e64 s[34:35], s86, v110
	s_and_b64 s[34:35], s[34:35], s[20:21]
	s_or_b64 s[16:17], s[16:17], s[34:35]
	s_sub_i32 s86, s86, s32
	s_max_i32 s86, s86, 0
	v_cmp_eq_u32_e64 s[20:21], s38, v75
	s_bcnt1_i32_b64 s32, s[20:21]
	s_nop 1
	v_mbcnt_lo_u32_b32 v110, s20, 0
	v_mbcnt_hi_u32_b32 v110, s21, v110
	v_cmp_gt_u32_e64 s[34:35], s86, v110
	s_and_b64 s[34:35], s[34:35], s[20:21]
	s_or_b64 s[18:19], s[18:19], s[34:35]
	s_sub_i32 s86, s86, s32
	s_max_i32 s86, s86, 0
	s_nop 1
	v_writelane_b32 v96, s12, 8
	v_writelane_b32 v97, s13, 8
	v_writelane_b32 v96, s14, 9
	v_writelane_b32 v97, s15, 9
	v_writelane_b32 v96, s16, 10
	v_writelane_b32 v97, s17, 10
	v_writelane_b32 v96, s18, 11
	v_writelane_b32 v97, s19, 11
	s_mov_b32 s38, 0
	s_mov_b32 s39, 0x40000000
; __device__ __forceinline__ void nsa_attn_phase(unsigned char* big, bf16_t* outO, LAS unsigned char* lds) {
;     ...
;                 for (int rr = 0; rr < 13; ++rr) {
;                     float best[8]; int bj[8];
; #pragma unroll
;                     for (int qq = 0; qq < 8; ++qq) {
;                         best[qq] = v0[qq]; bj[qq] = lane;
;                         if (v1[qq] > best[qq]) { best[qq] = v1[qq]; bj[qq] = lane + 64; }
;                         if (v2[qq] > best[qq]) { best[qq] = v2[qq]; bj[qq] = lane + 128; }
;                         if (v3[qq] > best[qq]) { best[qq] = v3[qq]; bj[qq] = lane + 192; }
;                     }
; #pragma unroll
;                     for (int off = 32; off >= 1; off >>= 1) {
;                         float ov[8]; int oj[8];
; #pragma unroll
;                         for (int qq = 0; qq < 8; ++qq) { ov[qq] = __shfl_xor(best[qq], off); oj[qq] = __shfl_xor(bj[qq], off); }
; #pragma unroll
;                         for (int qq = 0; qq < 8; ++qq) if (ov[qq] > best[qq] || (ov[qq] == best[qq] && oj[qq] < bj[qq])) { best[qq] = ov[qq]; bj[qq] = oj[qq]; }
;                     }
; #pragma unroll
;                     for (int qq = 0; qq < 8; ++qq) if ((bj[qq] & 63) == lane) { const int e = bj[qq] >> 6;
;                         if (e == 0) { v0[qq] = -2.f; sb[qq] |= 1u; } else if (e == 1) { v1[qq] = -2.f; sb[qq] |= 2u; } else if (e == 2) { v2[qq] = -2.f; sb[qq] |= 4u; } else { v3[qq] = -2.f; sb[qq] |= 8u; } }
;                 }
.Ltk_q3:
	s_or_b32 s50, s38, s39
	v_cmp_le_i32_e64 s[12:13], s50, v76
	v_cmp_le_i32_e64 s[14:15], s50, v77
	v_cmp_le_i32_e64 s[16:17], s50, v78
	v_cmp_le_i32_e64 s[18:19], s50, v79
	s_bcnt1_i32_b64 s51, s[12:13]
	s_bcnt1_i32_b64 s32, s[14:15]
	s_add_i32 s51, s51, s32
	s_bcnt1_i32_b64 s32, s[16:17]
	s_add_i32 s51, s51, s32
	s_bcnt1_i32_b64 s32, s[18:19]
	s_add_i32 s51, s51, s32
	s_cmp_ge_u32 s51, 16
	s_cselect_b32 s38, s50, s38
	s_lshr_b32 s39, s39, 1
	s_cmp_lg_u32 s39, 0
	s_cbranch_scc1 .Ltk_q3
	v_cmp_lt_i32_e64 s[12:13], s38, v76
	v_cmp_lt_i32_e64 s[14:15], s38, v77
	v_cmp_lt_i32_e64 s[16:17], s38, v78
	v_cmp_lt_i32_e64 s[18:19], s38, v79
	s_bcnt1_i32_b64 s51, s[12:13]
	s_bcnt1_i32_b64 s32, s[14:15]
	s_add_i32 s51, s51, s32
	s_bcnt1_i32_b64 s32, s[16:17]
	s_add_i32 s51, s51, s32
	s_bcnt1_i32_b64 s32, s[18:19]
	s_add_i32 s51, s51, s32
	s_sub_i32 s86, 16, s51
	v_cmp_eq_u32_e64 s[20:21], s38, v76
	s_bcnt1_i32_b64 s32, s[20:21]
	s_nop 1
	v_mbcnt_lo_u32_b32 v110, s20, 0
	v_mbcnt_hi_u32_b32 v110, s21, v110
	v_cmp_gt_u32_e64 s[34:35], s86, v110
	s_and_b64 s[34:35], s[34:35], s[20:21]
	s_or_b64 s[12:13], s[12:13], s[34:35]
	s_sub_i32 s86, s86, s32
	s_max_i32 s86, s86, 0
	v_cmp_eq_u32_e64 s[20:21], s38, v77
	s_bcnt1_i32_b64 s32, s[20:21]
	s_nop 1
	v_mbcnt_lo_u32_b32 v110, s20, 0
	v_mbcnt_hi_u32_b32 v110, s21, v110
	v_cmp_gt_u32_e64 s[34:35], s86, v110
	s_and_b64 s[34:35], s[34:35], s[20:21]
	s_or_b64 s[14:15], s[14:15], s[34:35]
	s_sub_i32 s86, s86, s32
	s_max_i32 s86, s86, 0
	v_cmp_eq_u32_e64 s[20:21], s38, v78
	s_bcnt1_i32_b64 s32, s[20:21]
	s_nop 1
	v_mbcnt_lo_u32_b32 v110, s20, 0
	v_mbcnt_hi_u32_b32 v110, s21, v110
	v_cmp_gt_u32_e64 s[34:35], s86, v110
	s_and_b64 s[34:35], s[34:35], s[20:21]
	s_or_b64 s[16:17], s[16:17], s[34:35]
	s_sub_i32 s86, s86, s32
	s_max_i32 s86, s86, 0
	v_cmp_eq_u32_e64 s[20:21], s38, v79
	s_bcnt1_i32_b64 s32, s[20:21]
	s_nop 1
	v_mbcnt_lo_u32_b32 v110, s20, 0
	v_mbcnt_hi_u32_b32 v110, s21, v110
	v_cmp_gt_u32_e64 s[34:35], s86, v110
	s_and_b64 s[34:35], s[34:35], s[20:21]
	s_or_b64 s[18:19], s[18:19], s[34:35]
	s_sub_i32 s86, s86, s32
	s_max_i32 s86, s86, 0
	s_nop 1
	v_writelane_b32 v96, s12, 12
	v_writelane_b32 v97, s13, 12
	v_writelane_b32 v96, s14, 13
	v_writelane_b32 v97, s15, 13
	v_writelane_b32 v96, s16, 14
	v_writelane_b32 v97, s17, 14
	v_writelane_b32 v96, s18, 15
	v_writelane_b32 v97, s19, 15
	s_mov_b32 s38, 0
	s_mov_b32 s39, 0x40000000
.Ltk_q4:
	s_or_b32 s50, s38, s39
	v_cmp_le_i32_e64 s[12:13], s50, v80
	v_cmp_le_i32_e64 s[14:15], s50, v81
	v_cmp_le_i32_e64 s[16:17], s50, v82
	v_cmp_le_i32_e64 s[18:19], s50, v83
	s_bcnt1_i32_b64 s51, s[12:13]
	s_bcnt1_i32_b64 s32, s[14:15]
	s_add_i32 s51, s51, s32
	s_bcnt1_i32_b64 s32, s[16:17]
	s_add_i32 s51, s51, s32
	s_bcnt1_i32_b64 s32, s[18:19]
	s_add_i32 s51, s51, s32
	s_cmp_ge_u32 s51, 16
	s_cselect_b32 s38, s50, s38
	s_lshr_b32 s39, s39, 1
	s_cmp_lg_u32 s39, 0
	s_cbranch_scc1 .Ltk_q4
	v_cmp_lt_i32_e64 s[12:13], s38, v80
	v_cmp_lt_i32_e64 s[14:15], s38, v81
	v_cmp_lt_i32_e64 s[16:17], s38, v82
	v_cmp_lt_i32_e64 s[18:19], s38, v83
	s_bcnt1_i32_b64 s51, s[12:13]
	s_bcnt1_i32_b64 s32, s[14:15]
	s_add_i32 s51, s51, s32
	s_bcnt1_i32_b64 s32, s[16:17]
	s_add_i32 s51, s51, s32
	s_bcnt1_i32_b64 s32, s[18:19]
	s_add_i32 s51, s51, s32
	s_sub_i32 s86, 16, s51
	v_cmp_eq_u32_e64 s[20:21], s38, v80
	s_bcnt1_i32_b64 s32, s[20:21]
	s_nop 1
	v_mbcnt_lo_u32_b32 v110, s20, 0
	v_mbcnt_hi_u32_b32 v110, s21, v110
	v_cmp_gt_u32_e64 s[34:35], s86, v110
	s_and_b64 s[34:35], s[34:35], s[20:21]
	s_or_b64 s[12:13], s[12:13], s[34:35]
	s_sub_i32 s86, s86, s32
	s_max_i32 s86, s86, 0
	v_cmp_eq_u32_e64 s[20:21], s38, v81
	s_bcnt1_i32_b64 s32, s[20:21]
	s_nop 1
	v_mbcnt_lo_u32_b32 v110, s20, 0
	v_mbcnt_hi_u32_b32 v110, s21, v110
	v_cmp_gt_u32_e64 s[34:35], s86, v110
	s_and_b64 s[34:35], s[34:35], s[20:21]
	s_or_b64 s[14:15], s[14:15], s[34:35]
	s_sub_i32 s86, s86, s32
	s_max_i32 s86, s86, 0
	v_cmp_eq_u32_e64 s[20:21], s38, v82
	s_bcnt1_i32_b64 s32, s[20:21]
	s_nop 1
	v_mbcnt_lo_u32_b32 v110, s20, 0
	v_mbcnt_hi_u32_b32 v110, s21, v110
	v_cmp_gt_u32_e64 s[34:35], s86, v110
	s_and_b64 s[34:35], s[34:35], s[20:21]
	s_or_b64 s[16:17], s[16:17], s[34:35]
	s_sub_i32 s86, s86, s32
	s_max_i32 s86, s86, 0
	v_cmp_eq_u32_e64 s[20:21], s38, v83
	s_bcnt1_i32_b64 s32, s[20:21]
	s_nop 1
	v_mbcnt_lo_u32_b32 v110, s20, 0
	v_mbcnt_hi_u32_b32 v110, s21, v110
	v_cmp_gt_u32_e64 s[34:35], s86, v110
	s_and_b64 s[34:35], s[34:35], s[20:21]
	s_or_b64 s[18:19], s[18:19], s[34:35]
	s_sub_i32 s86, s86, s32
	s_max_i32 s86, s86, 0
	s_nop 1
	v_writelane_b32 v96, s12, 16
	v_writelane_b32 v97, s13, 16
	v_writelane_b32 v96, s14, 17
	v_writelane_b32 v97, s15, 17
	v_writelane_b32 v96, s16, 18
	v_writelane_b32 v97, s17, 18
	v_writelane_b32 v96, s18, 19
	v_writelane_b32 v97, s19, 19
	s_mov_b32 s38, 0
	s_mov_b32 s39, 0x40000000
; __device__ __forceinline__ void nsa_attn_phase(unsigned char* big, bf16_t* outO, LAS unsigned char* lds) {
;     ...
;                 for (int rr = 0; rr < 13; ++rr) {
;                     float best[8]; int bj[8];
; #pragma unroll
;                     for (int qq = 0; qq < 8; ++qq) {
;                         best[qq] = v0[qq]; bj[qq] = lane;
;                         if (v1[qq] > best[qq]) { best[qq] = v1[qq]; bj[qq] = lane + 64; }
;                         if (v2[qq] > best[qq]) { best[qq] = v2[qq]; bj[qq] = lane + 128; }
;                         if (v3[qq] > best[qq]) { best[qq] = v3[qq]; bj[qq] = lane + 192; }
;                     }
; #pragma unroll
;                     for (int off = 32; off >= 1; off >>= 1) {
;                         float ov[8]; int oj[8];
; #pragma unroll
;                         for (int qq = 0; qq < 8; ++qq) { ov[qq] = __shfl_xor(best[qq], off); oj[qq] = __shfl_xor(bj[qq], off); }
; #pragma unroll
;                         for (int qq = 0; qq < 8; ++qq) if (ov[qq] > best[qq] || (ov[qq] == best[qq] && oj[qq] < bj[qq])) { best[qq] = ov[qq]; bj[qq] = oj[qq]; }
;                     }
; #pragma unroll
;                     for (int qq = 0; qq < 8; ++qq) if ((bj[qq] & 63) == lane) { const int e = bj[qq] >> 6;
;                         if (e == 0) { v0[qq] = -2.f; sb[qq] |= 1u; } else if (e == 1) { v1[qq] = -2.f; sb[qq] |= 2u; } else if (e == 2) { v2[qq] = -2.f; sb[qq] |= 4u; } else { v3[qq] = -2.f; sb[qq] |= 8u; } }
;                 }
.Ltk_q5:
	s_or_b32 s50, s38, s39
	v_cmp_le_i32_e64 s[12:13], s50, v84
	v_cmp_le_i32_e64 s[14:15], s50, v85
	v_cmp_le_i32_e64 s[16:17], s50, v86
	v_cmp_le_i32_e64 s[18:19], s50, v87
	s_bcnt1_i32_b64 s51, s[12:13]
	s_bcnt1_i32_b64 s32, s[14:15]
	s_add_i32 s51, s51, s32
	s_bcnt1_i32_b64 s32, s[16:17]
	s_add_i32 s51, s51, s32
	s_bcnt1_i32_b64 s32, s[18:19]
	s_add_i32 s51, s51, s32
	s_cmp_ge_u32 s51, 16
	s_cselect_b32 s38, s50, s38
	s_lshr_b32 s39, s39, 1
	s_cmp_lg_u32 s39, 0
	s_cbranch_scc1 .Ltk_q5
	v_cmp_lt_i32_e64 s[12:13], s38, v84
	v_cmp_lt_i32_e64 s[14:15], s38, v85
	v_cmp_lt_i32_e64 s[16:17], s38, v86
	v_cmp_lt_i32_e64 s[18:19], s38, v87
	s_bcnt1_i32_b64 s51, s[12:13]
	s_bcnt1_i32_b64 s32, s[14:15]
	s_add_i32 s51, s51, s32
	s_bcnt1_i32_b64 s32, s[16:17]
	s_add_i32 s51, s51, s32
	s_bcnt1_i32_b64 s32, s[18:19]
	s_add_i32 s51, s51, s32
	s_sub_i32 s86, 16, s51
	v_cmp_eq_u32_e64 s[20:21], s38, v84
	s_bcnt1_i32_b64 s32, s[20:21]
	s_nop 1
	v_mbcnt_lo_u32_b32 v110, s20, 0
	v_mbcnt_hi_u32_b32 v110, s21, v110
	v_cmp_gt_u32_e64 s[34:35], s86, v110
	s_and_b64 s[34:35], s[34:35], s[20:21]
	s_or_b64 s[12:13], s[12:13], s[34:35]
	s_sub_i32 s86, s86, s32
	s_max_i32 s86, s86, 0
	v_cmp_eq_u32_e64 s[20:21], s38, v85
	s_bcnt1_i32_b64 s32, s[20:21]
	s_nop 1
	v_mbcnt_lo_u32_b32 v110, s20, 0
	v_mbcnt_hi_u32_b32 v110, s21, v110
	v_cmp_gt_u32_e64 s[34:35], s86, v110
	s_and_b64 s[34:35], s[34:35], s[20:21]
	s_or_b64 s[14:15], s[14:15], s[34:35]
	s_sub_i32 s86, s86, s32
	s_max_i32 s86, s86, 0
	v_cmp_eq_u32_e64 s[20:21], s38, v86
	s_bcnt1_i32_b64 s32, s[20:21]
	s_nop 1
	v_mbcnt_lo_u32_b32 v110, s20, 0
	v_mbcnt_hi_u32_b32 v110, s21, v110
	v_cmp_gt_u32_e64 s[34:35], s86, v110
	s_and_b64 s[34:35], s[34:35], s[20:21]
	s_or_b64 s[16:17], s[16:17], s[34:35]
	s_sub_i32 s86, s86, s32
	s_max_i32 s86, s86, 0
	v_cmp_eq_u32_e64 s[20:21], s38, v87
	s_bcnt1_i32_b64 s32, s[20:21]
	s_nop 1
	v_mbcnt_lo_u32_b32 v110, s20, 0
	v_mbcnt_hi_u32_b32 v110, s21, v110
	v_cmp_gt_u32_e64 s[34:35], s86, v110
	s_and_b64 s[34:35], s[34:35], s[20:21]
	s_or_b64 s[18:19], s[18:19], s[34:35]
	s_sub_i32 s86, s86, s32
	s_max_i32 s86, s86, 0
	s_nop 1
	v_writelane_b32 v96, s12, 20
	v_writelane_b32 v97, s13, 20
	v_writelane_b32 v96, s14, 21
	v_writelane_b32 v97, s15, 21
	v_writelane_b32 v96, s16, 22
	v_writelane_b32 v97, s17, 22
	v_writelane_b32 v96, s18, 23
	v_writelane_b32 v97, s19, 23
	s_mov_b32 s38, 0
	s_mov_b32 s39, 0x40000000
.Ltk_q6:
	s_or_b32 s50, s38, s39
	v_cmp_le_i32_e64 s[12:13], s50, v88
	v_cmp_le_i32_e64 s[14:15], s50, v89
	v_cmp_le_i32_e64 s[16:17], s50, v90
	v_cmp_le_i32_e64 s[18:19], s50, v91
	s_bcnt1_i32_b64 s51, s[12:13]
	s_bcnt1_i32_b64 s32, s[14:15]
	s_add_i32 s51, s51, s32
	s_bcnt1_i32_b64 s32, s[16:17]
	s_add_i32 s51, s51, s32
	s_bcnt1_i32_b64 s32, s[18:19]
	s_add_i32 s51, s51, s32
	s_cmp_ge_u32 s51, 16
	s_cselect_b32 s38, s50, s38
	s_lshr_b32 s39, s39, 1
	s_cmp_lg_u32 s39, 0
	s_cbranch_scc1 .Ltk_q6
	v_cmp_lt_i32_e64 s[12:13], s38, v88
	v_cmp_lt_i32_e64 s[14:15], s38, v89
	v_cmp_lt_i32_e64 s[16:17], s38, v90
	v_cmp_lt_i32_e64 s[18:19], s38, v91
	s_bcnt1_i32_b64 s51, s[12:13]
	s_bcnt1_i32_b64 s32, s[14:15]
	s_add_i32 s51, s51, s32
	s_bcnt1_i32_b64 s32, s[16:17]
	s_add_i32 s51, s51, s32
	s_bcnt1_i32_b64 s32, s[18:19]
	s_add_i32 s51, s51, s32
	s_sub_i32 s86, 16, s51
	v_cmp_eq_u32_e64 s[20:21], s38, v88
	s_bcnt1_i32_b64 s32, s[20:21]
	s_nop 1
	v_mbcnt_lo_u32_b32 v110, s20, 0
	v_mbcnt_hi_u32_b32 v110, s21, v110
	v_cmp_gt_u32_e64 s[34:35], s86, v110
	s_and_b64 s[34:35], s[34:35], s[20:21]
	s_or_b64 s[12:13], s[12:13], s[34:35]
	s_sub_i32 s86, s86, s32
	s_max_i32 s86, s86, 0
	v_cmp_eq_u32_e64 s[20:21], s38, v89
	s_bcnt1_i32_b64 s32, s[20:21]
	s_nop 1
	v_mbcnt_lo_u32_b32 v110, s20, 0
	v_mbcnt_hi_u32_b32 v110, s21, v110
	v_cmp_gt_u32_e64 s[34:35], s86, v110
	s_and_b64 s[34:35], s[34:35], s[20:21]
	s_or_b64 s[14:15], s[14:15], s[34:35]
	s_sub_i32 s86, s86, s32
	s_max_i32 s86, s86, 0
	v_cmp_eq_u32_e64 s[20:21], s38, v90
	s_bcnt1_i32_b64 s32, s[20:21]
	s_nop 1
	v_mbcnt_lo_u32_b32 v110, s20, 0
	v_mbcnt_hi_u32_b32 v110, s21, v110
	v_cmp_gt_u32_e64 s[34:35], s86, v110
	s_and_b64 s[34:35], s[34:35], s[20:21]
	s_or_b64 s[16:17], s[16:17], s[34:35]
	s_sub_i32 s86, s86, s32
	s_max_i32 s86, s86, 0
	v_cmp_eq_u32_e64 s[20:21], s38, v91
	s_bcnt1_i32_b64 s32, s[20:21]
	s_nop 1
	v_mbcnt_lo_u32_b32 v110, s20, 0
	v_mbcnt_hi_u32_b32 v110, s21, v110
	v_cmp_gt_u32_e64 s[34:35], s86, v110
	s_and_b64 s[34:35], s[34:35], s[20:21]
	s_or_b64 s[18:19], s[18:19], s[34:35]
	s_sub_i32 s86, s86, s32
	s_max_i32 s86, s86, 0
	s_nop 1
	v_writelane_b32 v96, s12, 24
	v_writelane_b32 v97, s13, 24
	v_writelane_b32 v96, s14, 25
	v_writelane_b32 v97, s15, 25
	v_writelane_b32 v96, s16, 26
	v_writelane_b32 v97, s17, 26
	v_writelane_b32 v96, s18, 27
	v_writelane_b32 v97, s19, 27
	s_mov_b32 s38, 0
	s_mov_b32 s39, 0x40000000
; __device__ __forceinline__ void nsa_attn_phase(unsigned char* big, bf16_t* outO, LAS unsigned char* lds) {
;     ...
;                     for (int qq = 0; qq < 8; ++qq) if ((bj[qq] & 63) == lane) { const int e = bj[qq] >> 6;
;                         if (e == 0) { v0[qq] = -2.f; sb[qq] |= 1u; } else if (e == 1) { v1[qq] = -2.f; sb[qq] |= 2u; } else if (e == 2) { v2[qq] = -2.f; sb[qq] |= 4u; } else { v3[qq] = -2.f; sb[qq] |= 8u; } }
;                 }
;             }
; #pragma unroll
;             for (int qq = 0; qq < 8; ++qq) {
; #pragma unroll
;                 for (int e = 0; e < 4; ++e) { const int j = lane + 64 * e; const bool f = (cur < 16) ? (j <= cur) : (j == 0 || j == cur || j == cur - 1); if (f) sb[qq] |= (1u << e); }
; #pragma unroll
;                 for (int e = 0; e < 4; ++e) { const unsigned long long bal = __ballot((sb[qq] >> e) & 1u); if (lane == 0) { sel[(8 * w + qq) * 8 + 2 * e] = (unsigned)bal; sel[(8 * w + qq) * 8 + 2 * e + 1] = (unsigned)(bal >> 32); } }
;             }
.Ltk_q7:
	s_or_b32 s50, s38, s39
	v_cmp_le_i32_e64 s[12:13], s50, v92
	v_cmp_le_i32_e64 s[14:15], s50, v93
	v_cmp_le_i32_e64 s[16:17], s50, v94
	v_cmp_le_i32_e64 s[18:19], s50, v95
	s_bcnt1_i32_b64 s51, s[12:13]
	s_bcnt1_i32_b64 s32, s[14:15]
	s_add_i32 s51, s51, s32
	s_bcnt1_i32_b64 s32, s[16:17]
	s_add_i32 s51, s51, s32
	s_bcnt1_i32_b64 s32, s[18:19]
	s_add_i32 s51, s51, s32
	s_cmp_ge_u32 s51, 16
	s_cselect_b32 s38, s50, s38
	s_lshr_b32 s39, s39, 1
	s_cmp_lg_u32 s39, 0
	s_cbranch_scc1 .Ltk_q7
	v_cmp_lt_i32_e64 s[12:13], s38, v92
	v_cmp_lt_i32_e64 s[14:15], s38, v93
	v_cmp_lt_i32_e64 s[16:17], s38, v94
	v_cmp_lt_i32_e64 s[18:19], s38, v95
	s_bcnt1_i32_b64 s51, s[12:13]
	s_bcnt1_i32_b64 s32, s[14:15]
	s_add_i32 s51, s51, s32
	s_bcnt1_i32_b64 s32, s[16:17]
	s_add_i32 s51, s51, s32
	s_bcnt1_i32_b64 s32, s[18:19]
	s_add_i32 s51, s51, s32
	s_sub_i32 s86, 16, s51
	v_cmp_eq_u32_e64 s[20:21], s38, v92
	s_bcnt1_i32_b64 s32, s[20:21]
	s_nop 1
	v_mbcnt_lo_u32_b32 v110, s20, 0
	v_mbcnt_hi_u32_b32 v110, s21, v110
	v_cmp_gt_u32_e64 s[34:35], s86, v110
	s_and_b64 s[34:35], s[34:35], s[20:21]
	s_or_b64 s[12:13], s[12:13], s[34:35]
	s_sub_i32 s86, s86, s32
	s_max_i32 s86, s86, 0
	v_cmp_eq_u32_e64 s[20:21], s38, v93
	s_bcnt1_i32_b64 s32, s[20:21]
	s_nop 1
	v_mbcnt_lo_u32_b32 v110, s20, 0
	v_mbcnt_hi_u32_b32 v110, s21, v110
	v_cmp_gt_u32_e64 s[34:35], s86, v110
	s_and_b64 s[34:35], s[34:35], s[20:21]
	s_or_b64 s[14:15], s[14:15], s[34:35]
	s_sub_i32 s86, s86, s32
	s_max_i32 s86, s86, 0
	v_cmp_eq_u32_e64 s[20:21], s38, v94
	s_bcnt1_i32_b64 s32, s[20:21]
	s_nop 1
	v_mbcnt_lo_u32_b32 v110, s20, 0
	v_mbcnt_hi_u32_b32 v110, s21, v110
	v_cmp_gt_u32_e64 s[34:35], s86, v110
	s_and_b64 s[34:35], s[34:35], s[20:21]
	s_or_b64 s[16:17], s[16:17], s[34:35]
	s_sub_i32 s86, s86, s32
	s_max_i32 s86, s86, 0
	v_cmp_eq_u32_e64 s[20:21], s38, v95
	s_bcnt1_i32_b64 s32, s[20:21]
	s_nop 1
	v_mbcnt_lo_u32_b32 v110, s20, 0
	v_mbcnt_hi_u32_b32 v110, s21, v110
	v_cmp_gt_u32_e64 s[34:35], s86, v110
	s_and_b64 s[34:35], s[34:35], s[20:21]
	s_or_b64 s[18:19], s[18:19], s[34:35]
	s_sub_i32 s86, s86, s32
	s_max_i32 s86, s86, 0
	s_nop 1
	v_writelane_b32 v96, s12, 28
	v_writelane_b32 v97, s13, 28
	v_writelane_b32 v96, s14, 29
	v_writelane_b32 v97, s15, 29
	v_writelane_b32 v96, s16, 30
	v_writelane_b32 v97, s17, 30
	v_writelane_b32 v96, s18, 31
	v_writelane_b32 v97, s19, 31
	s_branch .Ltk_store
.Ltk_small:
	s_lshl_b32 s51, 2, s55
	s_add_i32 s51, s51, -1
	v_and_b32_e32 v111, 3, v151
	v_cmp_eq_u32_e32 vcc, 0, v111
	v_mov_b32_e32 v97, 0
	v_mov_b32_e32 v111, s51
	s_nop 1
	v_cndmask_b32_e32 v96, 0, v111, vcc
.Ltk_store:
	v_lshlrev_b32_e32 v98, 3, v151
	v_add3_u32 v98, v98, s71, v181
	s_mov_b32 exec_lo, -1
	s_mov_b32 exec_hi, 0
	ds_write_b64 v98, v[96:97]
	s_mov_b64 exec, -1
	s_branch .Ltk_done

;     __device__ __forceinline__ unsigned v_off(int row, int cc) const { return (unsigned)((size_t)row * vld + cc * 8) * 2u; }
;     __device__ __forceinline__ const char* v_ptr(int t, unsigned off) const { return (const char*)Vt + (size_t)t * 128 + off; }
;     __device__ __forceinline__ unsigned v_off(int row, int cc) const { return (unsigned)(row * S_ + cc * 8) * 2u; }
;     __device__ __forceinline__ const char* v_ptr(int t, unsigned off) const { return (const char*)Vt + (size_t)t * 128 + off; }
; template <int DQK, bool STATS, class Src>
; __device__ __forceinline__ void attn_preissue(LAS unsigned char* lk, LAS unsigned char* lv, int tb, int te, const Src& src) {
;     ...
;     if (!STATS) {
; #pragma unroll
;         for (int j = 0; j < (NIV + 7) / 8; ++j) { const int id = w + 8 * j; if (id < NIV) { const int qd = id * 64 + lane, row = qd / CPRV, cc = qd - row * CPRV;
;             glds16(src.v_ptr(tb, src.v_off(row, cc < 8 ? cc : 0)), __builtin_amdgcn_readfirstlane(lvA + id * 1024)); } }
;     }
.LBB0_1348:
	v_mul_hi_i32 v0, v34, s0
	v_lshrrev_b32_e32 v35, 31, v0
	v_ashrrev_i32_e32 v0, 1, v0
	v_add_u32_e32 v0, v0, v35
	v_mad_u64_u32 v[34:35], s[12:13], v0, -9, v[34:35]
	v_lshlrev_b32_e32 v35, 4, v34
	v_cmp_gt_i32_e32 vcc, 8, v34
	s_lshl_b32 s12, s16, 10
	s_add_i32 s12, s12, 0
	v_cndmask_b32_e32 v34, 0, v35, vcc
	v_lshl_add_u32 v0, v0, 15, v34
	v_lshl_add_u64 v[34:35], s[24:25], 0, v[0:1]
	s_add_i32 s12, s12, 0x8800
	s_mov_b32 s13, m0
	s_mov_b32 m0, s12
	s_nop 0
	global_load_lds_dwordx4 v[34:35], off
	s_mov_b32 m0, s13
	s_cmp_gt_i32 s14, 1
	s_cbranch_scc0 .LBB0_959
	s_branch .LBB0_960
.LBB0_1353:
	s_and_b64 vcc, exec, s[14:15]
	s_cbranch_vccnz .LBB0_853

; #define LAS __attribute__((address_space(3)))
; __device__ __forceinline__ unsigned lds_addr(const LAS void* p) { return (unsigned)(size_t)p; }
;     __device__ __forceinline__ unsigned k_off(int row, int cc) const { return (unsigned)(row * kld + cc * 8) * 2u; }
; template <int DQK, bool STATS, bool PRE, class Src, class Mask, class Post> ...
;     ...
;     const unsigned lkA = lds_addr(lk), lvA = lds_addr(lv);
;     unsigned koff[(NIK + 7) / 8], voff[(NIV + 7) / 8];
; #pragma unroll
;     for (int j_ = 0; j_ < (NIK + 7) / 8; ++j_) { const int id_ = w + 8 * j_; const int qd_ = id_ * 64 + lane, row_ = qd_ / CPRK, cc_ = qd_ - row_ * CPRK; koff[j_] = (id_ < NIK) ? src.k_off(row_, cc_ < KCH ? cc_ : 0) : 0u; }
; __device__ __forceinline__ void nsa_attn_phase(unsigned char* big, bf16_t* outO, LAS unsigned char* lds) {
;     ...
;         asm volatile("s_waitcnt lgkmcnt(0)" ::: "memory");
;         LAS u32x2* stash = (LAS u32x2*)impw + lane;
; #pragma unroll
;         for (int k = 0; k < 16; ++k) stash[k * 64] = oc[k];
;         acc_reset(a);
.Ltk_done:
	s_waitcnt lgkmcnt(0)
	ds_write2st64_b64 v179, v[2:3], v[4:5] offset1:1
	ds_write2st64_b64 v179, v[6:7], v[8:9] offset0:2 offset1:3
	ds_write2st64_b64 v179, v[10:11], v[12:13] offset0:4 offset1:5
	ds_write2st64_b64 v179, v[14:15], v[16:17] offset0:6 offset1:7
	ds_write2st64_b64 v179, v[18:19], v[20:21] offset0:8 offset1:9
	ds_write2st64_b64 v179, v[22:23], v[24:25] offset0:10 offset1:11
	ds_write2st64_b64 v179, v[26:27], v[28:29] offset0:12 offset1:13
	ds_write2st64_b64 v179, v[30:31], v[32:33] offset0:14 offset1:15
	v_mov_b32_e32 v3, v192
	v_mov_b64_e32 v[16:17], 0
	v_readfirstlane_b32 s12, v3
	s_ashr_i32 s35, s12, 6
	s_cmp_lt_i32 s35, 17
	v_and_b32_e32 v4, 63, v3
	s_cselect_b64 s[14:15], -1, 0
	s_cmp_gt_i32 s35, 16
	v_mov_b64_e32 v[18:19], 0
	s_cbranch_scc1 .LBB0_1738
	s_and_b32 s13, s12, 0xffffffc0
	v_or_b32_e32 v0, s13, v4
	v_mul_hi_i32 v2, v0, s60
	v_lshrrev_b32_e32 v5, 31, v2
	v_ashrrev_i32_e32 v2, 3, v2
	v_add_u32_e32 v2, v2, v5
	v_mad_u64_u32 v[6:7], s[16:17], v2, s61, v[0:1]
	v_lshlrev_b32_e32 v0, 4, v6
	v_cmp_gt_i32_e32 vcc, 16, v6
	s_nop 1
	v_cndmask_b32_e32 v0, 0, v0, vcc
	v_lshl_add_u32 v0, v2, 8, v0
	v_mov_b64_e32 v[18:19], v[0:1]
